# v5 + P5 gated-merge loop: two iterations per trip (8 loads in flight per thread)
# baseline (speedup 1.0000x reference)
; __device__ __forceinline__ unsigned pk2(float lo, float hi) { typedef float f2_ __attribute__((ext_vector_type(2))); const bf16x2n_t b = __builtin_convertvector((f2_){lo, hi}, bf16x2n_t); return __builtin_bit_cast(unsigned, b); }
; __device__ __forceinline__ float bflo(unsigned w) { return __uint_as_float(w << 16); }
; __device__ __forceinline__ float bfhi(unsigned w) { return __uint_as_float(w & 0xffff0000u); }
; template <unsigned MASK> __global__ void __launch_bounds__(NTHREADS, 2) fwd(Args A0) {
;     ...
;             for (size_t i = (size_t)F.bid * NTHREADS + F.tid; i < n8; i += stride) {
;                 f32x4 lo4 = (f32x4){0.f, 0.f, 0.f, 0.f}, hi4 = lo4;
; #pragma unroll
;                 for (int z = 0; z < 4; ++z) { const u32x4 w = *(const u32x4*)(PG + (size_t)z * M * D + 8 * i);
;                     lo4[0] += bflo(w.x); lo4[1] += bfhi(w.x); lo4[2] += bflo(w.y); lo4[3] += bfhi(w.y); hi4[0] += bflo(w.z); hi4[1] += bfhi(w.z); hi4[2] += bflo(w.w); hi4[3] += bfhi(w.w); }
;                 u32x4 o; o.x = pk2(lo4[0], lo4[1]); o.y = pk2(lo4[2], lo4[3]); o.z = pk2(hi4[0], hi4[1]); o.w = pk2(hi4[2], hi4[3]);
;                 *(u32x4*)(Gm + 8 * i) = o; }
.LBB0_1810:
	v_lshl_add_u64 v[44:45], v[0:1], 0, s[4:5]
	s_mov_b64 s[10:11], 0x280000
	v_cmp_gt_u64_e64 s[100:101], s[10:11], v[44:45]
	s_cmp_eq_u64 s[100:101], 0
	s_cbranch_scc1 .Lp5_single
	v_lshl_add_u64 v[44:45], v[2:3], 0, s[6:7]
	v_lshl_add_u64 v[0:1], v[0:1], 0, s[4:5]
	v_lshl_add_u64 v[0:1], v[0:1], 0, s[4:5]
	v_add_co_u32_e32 v4, vcc, 0x5000000, v2
	s_nop 0
	s_nop 0
	v_addc_co_u32_e32 v5, vcc, 0, v3, vcc
	v_add_co_u32_e32 v8, vcc, 0x7800000, v2
	global_load_dwordx4 v[4:7], v[4:5], off
	s_nop 0
	v_addc_co_u32_e32 v9, vcc, 0, v3, vcc
	v_add_co_u32_e32 v12, vcc, 0xa000000, v2
	global_load_dwordx4 v[8:11], v[8:9], off
	s_nop 0
	v_addc_co_u32_e32 v13, vcc, 0, v3, vcc
	v_add_co_u32_e32 v16, vcc, 0xc800000, v2
	global_load_dwordx4 v[12:15], v[12:13], off
	s_nop 0
	v_addc_co_u32_e32 v17, vcc, 0, v3, vcc
	global_load_dwordx4 v[16:19], v[16:17], off
	v_add_co_u32_e32 v24, vcc, 0x5000000, v44
	s_nop 0
	s_nop 0
	v_addc_co_u32_e32 v25, vcc, 0, v45, vcc
	v_add_co_u32_e32 v28, vcc, 0x7800000, v44
	global_load_dwordx4 v[24:27], v[24:25], off
	s_nop 0
	v_addc_co_u32_e32 v29, vcc, 0, v45, vcc
	v_add_co_u32_e32 v32, vcc, 0xa000000, v44
	global_load_dwordx4 v[28:31], v[28:29], off
	s_nop 0
	v_addc_co_u32_e32 v33, vcc, 0, v45, vcc
	v_add_co_u32_e32 v36, vcc, 0xc800000, v44
	global_load_dwordx4 v[32:35], v[32:33], off
	s_nop 0
	v_addc_co_u32_e32 v37, vcc, 0, v45, vcc
	global_load_dwordx4 v[36:39], v[36:37], off
	s_mov_b64 s[10:11], 0x27ffff
	v_cmp_lt_u64_e32 vcc, s[10:11], v[0:1]
	s_or_b64 s[8:9], vcc, s[8:9]
	s_waitcnt vmcnt(4)
	v_lshlrev_b32_e32 v20, 16, v4
	v_and_b32_e32 v21, 0xffff0000, v4
	v_lshlrev_b32_e32 v4, 16, v5
	v_and_b32_e32 v5, 0xffff0000, v5
	v_pk_add_f32 v[4:5], v[4:5], 0 op_sel_hi:[1,0]
	v_lshlrev_b32_e32 v22, 16, v8
	v_and_b32_e32 v23, 0xffff0000, v8
	v_lshlrev_b32_e32 v8, 16, v9
	v_and_b32_e32 v9, 0xffff0000, v9
	v_pk_add_f32 v[4:5], v[4:5], v[8:9]
	v_lshlrev_b32_e32 v8, 16, v13
	v_and_b32_e32 v9, 0xffff0000, v13
	v_pk_add_f32 v[4:5], v[4:5], v[8:9]
	v_lshlrev_b32_e32 v8, 16, v17
	v_and_b32_e32 v9, 0xffff0000, v17
	v_pk_add_f32 v[20:21], v[20:21], 0 op_sel_hi:[1,0]
	v_pk_add_f32 v[8:9], v[4:5], v[8:9]
	v_lshlrev_b32_e32 v4, 16, v6
	v_and_b32_e32 v5, 0xffff0000, v6
	v_pk_add_f32 v[20:21], v[20:21], v[22:23]
	v_lshlrev_b32_e32 v22, 16, v12
	v_and_b32_e32 v23, 0xffff0000, v12
	v_pk_add_f32 v[4:5], v[4:5], 0 op_sel_hi:[1,0]
	v_lshlrev_b32_e32 v12, 16, v10
	v_and_b32_e32 v13, 0xffff0000, v10
	v_pk_add_f32 v[4:5], v[4:5], v[12:13]
	v_lshlrev_b32_e32 v12, 16, v14
	v_and_b32_e32 v13, 0xffff0000, v14
	v_pk_add_f32 v[4:5], v[4:5], v[12:13]
	v_lshlrev_b32_e32 v12, 16, v18
	v_and_b32_e32 v13, 0xffff0000, v18
	v_pk_add_f32 v[12:13], v[4:5], v[12:13]
	v_lshlrev_b32_e32 v4, 16, v7
	v_and_b32_e32 v5, 0xffff0000, v7
	v_pk_add_f32 v[4:5], v[4:5], 0 op_sel_hi:[1,0]
	v_lshlrev_b32_e32 v6, 16, v11
	v_and_b32_e32 v7, 0xffff0000, v11
	v_pk_add_f32 v[4:5], v[4:5], v[6:7]
	v_lshlrev_b32_e32 v6, 16, v15
	v_and_b32_e32 v7, 0xffff0000, v15
	v_pk_add_f32 v[20:21], v[20:21], v[22:23]
	v_lshlrev_b32_e32 v22, 16, v16
	v_and_b32_e32 v23, 0xffff0000, v16
	v_pk_add_f32 v[4:5], v[4:5], v[6:7]
	v_lshlrev_b32_e32 v6, 16, v19
	v_and_b32_e32 v7, 0xffff0000, v19
	v_pk_add_f32 v[20:21], v[20:21], v[22:23]
	v_pk_add_f32 v[10:11], v[4:5], v[6:7]
	v_cvt_pk_bf16_f32 v4, v20, v21
	v_cvt_pk_bf16_f32 v5, v8, v9
	v_cvt_pk_bf16_f32 v6, v12, v13
	v_cvt_pk_bf16_f32 v7, v10, v11
	global_store_dwordx4 v[2:3], v[4:7], off
	s_waitcnt vmcnt(1)
	v_lshlrev_b32_e32 v40, 16, v24
	v_and_b32_e32 v41, 0xffff0000, v24
	v_lshlrev_b32_e32 v24, 16, v25
	v_and_b32_e32 v25, 0xffff0000, v25
	v_pk_add_f32 v[24:25], v[24:25], 0 op_sel_hi:[1,0]
	v_lshlrev_b32_e32 v42, 16, v28
	v_and_b32_e32 v43, 0xffff0000, v28
	v_lshlrev_b32_e32 v28, 16, v29
	v_and_b32_e32 v29, 0xffff0000, v29
	v_pk_add_f32 v[24:25], v[24:25], v[28:29]
	v_lshlrev_b32_e32 v28, 16, v33
	v_and_b32_e32 v29, 0xffff0000, v33
	v_pk_add_f32 v[24:25], v[24:25], v[28:29]
	v_lshlrev_b32_e32 v28, 16, v37
	v_and_b32_e32 v29, 0xffff0000, v37
	v_pk_add_f32 v[40:41], v[40:41], 0 op_sel_hi:[1,0]
	v_pk_add_f32 v[28:29], v[24:25], v[28:29]
	v_lshlrev_b32_e32 v24, 16, v26
	v_and_b32_e32 v25, 0xffff0000, v26
	v_pk_add_f32 v[40:41], v[40:41], v[42:43]
	v_lshlrev_b32_e32 v42, 16, v32
	v_and_b32_e32 v43, 0xffff0000, v32
	v_pk_add_f32 v[24:25], v[24:25], 0 op_sel_hi:[1,0]
	v_lshlrev_b32_e32 v32, 16, v30
	v_and_b32_e32 v33, 0xffff0000, v30
	v_pk_add_f32 v[24:25], v[24:25], v[32:33]
	v_lshlrev_b32_e32 v32, 16, v34
	v_and_b32_e32 v33, 0xffff0000, v34
	v_pk_add_f32 v[24:25], v[24:25], v[32:33]
	v_lshlrev_b32_e32 v32, 16, v38
	v_and_b32_e32 v33, 0xffff0000, v38
	v_pk_add_f32 v[32:33], v[24:25], v[32:33]
	v_lshlrev_b32_e32 v24, 16, v27
	v_and_b32_e32 v25, 0xffff0000, v27
	v_pk_add_f32 v[24:25], v[24:25], 0 op_sel_hi:[1,0]
	v_lshlrev_b32_e32 v26, 16, v31
	v_and_b32_e32 v27, 0xffff0000, v31
	v_pk_add_f32 v[24:25], v[24:25], v[26:27]
	v_lshlrev_b32_e32 v26, 16, v35
	v_and_b32_e32 v27, 0xffff0000, v35
	v_pk_add_f32 v[40:41], v[40:41], v[42:43]
	v_lshlrev_b32_e32 v42, 16, v36
	v_and_b32_e32 v43, 0xffff0000, v36
	v_pk_add_f32 v[24:25], v[24:25], v[26:27]
	v_lshlrev_b32_e32 v26, 16, v39
	v_and_b32_e32 v27, 0xffff0000, v39
	v_pk_add_f32 v[40:41], v[40:41], v[42:43]
	v_pk_add_f32 v[30:31], v[24:25], v[26:27]
	v_cvt_pk_bf16_f32 v24, v40, v41
	v_cvt_pk_bf16_f32 v25, v28, v29
	v_cvt_pk_bf16_f32 v26, v32, v33
	v_cvt_pk_bf16_f32 v27, v30, v31
	global_store_dwordx4 v[44:45], v[24:27], off
	v_lshl_add_u64 v[2:3], v[44:45], 0, s[6:7]
	s_andn2_b64 exec, exec, s[8:9]
	s_cbranch_execnz .LBB0_1810
	s_branch .Lp5_done

; __device__ __forceinline__ unsigned xb_ld(unsigned* p)              { return __hip_atomic_load(p, __ATOMIC_RELAXED, __HIP_MEMORY_SCOPE_AGENT); }
; __device__ __forceinline__ unsigned xb_add(unsigned* p, unsigned v) { return __hip_atomic_fetch_add(p, v, __ATOMIC_RELAXED, __HIP_MEMORY_SCOPE_AGENT); }
; #define XB_SPIN(cond, bar) do { unsigned _sp = 0; while (cond) { __builtin_amdgcn_s_sleep(1); \
;     if ((++_sp & 255u) == 0u) { if (xb_ld(&(bar)[XB_TMO])) break; if (_sp > XB_SPIN_CAP) { atomicAdd(&(bar)[XB_TMO], 1u); break; } } } } while (0)
; __device__ __forceinline__ void xcd_barrier(const XcdBarrier& b) {
;     asm volatile("s_waitcnt vmcnt(0)" ::: "memory");
;     __syncthreads();
;     if (threadIdx.x == 0) {
;         unsigned* bar = b.bar; unsigned bx = b.x; asm volatile("" : "+s"(bar), "+s"(bx));
;         __builtin_amdgcn_s_waitcnt(0);
;         const unsigned nloc = b.st[0], nx = b.st[1];
;         const unsigned old = xb_add(&bar[XB_XSUB(bx)], 1u);
;         const unsigned gen = old / nloc;
;         if (old + 1u == (gen + 1u) * nloc) {
;             __builtin_amdgcn_fence(__ATOMIC_RELEASE, "agent");
;             asm volatile("s_waitcnt vmcnt(0)" ::: "memory");
;             const unsigned og = xb_add(&bar[XB_TOP], 1u);
;             const unsigned tg = og / nx;
;             if (og + 1u == (tg + 1u) * nx) xb_add(&bar[XB_TOPGEN], 1u);
;             else XB_SPIN(xb_ld(&bar[XB_TOPGEN]) == tg, bar);
;             __builtin_amdgcn_fence(__ATOMIC_ACQUIRE, "agent");
;             xb_add(&bar[XB_XGEN(bx)], 1u);
;             asm volatile("s_waitcnt vmcnt(0)" ::: "memory");
;         } else {
;             XB_SPIN(xb_ld(&bar[XB_XGEN(bx)]) == gen, bar);
;             __builtin_amdgcn_fence(__ATOMIC_ACQUIRE, "agent");
;             asm volatile("s_waitcnt vmcnt(0)" ::: "memory");
.Lp5_done:
.LBB0_1811:
	s_or_b64 exec, exec, s[0:1]
	v_readlane_b32 s0, v254, 16
	v_readlane_b32 s1, v254, 17
	s_xor_b64 s[40:41], s[0:1], -1
	v_readlane_b32 s0, v254, 14
	s_waitcnt vmcnt(0)
	v_readlane_b32 s1, v254, 15
	s_xor_b64 s[38:39], s[0:1], -1
	s_barrier
	s_mov_b64 s[0:1], exec
	v_readlane_b32 s4, v254, 7
	v_readlane_b32 s5, v254, 8
	s_and_b64 s[4:5], s[0:1], s[4:5]
	s_mov_b64 exec, s[4:5]
	s_cbranch_execz .LBB0_1841
	v_readlane_b32 s4, v254, 4
	v_readlane_b32 s6, v254, 6
	v_readlane_b32 s5, v254, 5
	v_readlane_b32 s7, v254, 10
	s_lshl_b32 s26, s6, 6
	s_add_i32 s70, s26, 0x500
	v_mov_b32_e32 v0, s7
	v_readlane_b32 s7, v254, 11
	s_waitcnt vmcnt(0) expcnt(0) lgkmcnt(0)
	ds_read_b32 v4, v0
	v_mov_b32_e32 v0, s7
	s_lshl_b64 s[6:7], s[70:71], 2
	s_add_u32 s6, s4, s6
	s_addc_u32 s7, s5, s7
	ds_read_b32 v1, v0
	v_mov_b64_e32 v[2:3], s[6:7]
	v_mov_b32_e32 v0, 1
	flat_atomic_add v2, v[2:3], v0 sc0
	s_waitcnt lgkmcnt(0)
	v_cvt_f32_u32_e32 v0, v4
	v_sub_u32_e32 v3, 0, v4
	v_rcp_iflag_f32_e32 v0, v0
	s_nop 0
	v_mul_f32_e32 v0, 0x4f7ffffe, v0
	v_cvt_u32_f32_e32 v0, v0
	v_mul_lo_u32 v3, v3, v0
	v_mul_hi_u32 v3, v0, v3
	v_add_u32_e32 v0, v0, v3
	s_waitcnt vmcnt(0)
	v_mul_hi_u32 v0, v2, v0
	v_mul_lo_u32 v3, v0, v4
	v_sub_u32_e32 v3, v2, v3
	v_add_u32_e32 v5, 1, v0
	v_cmp_ge_u32_e32 vcc, v3, v4
	v_add_u32_e32 v2, 1, v2
	s_nop 0
	v_cndmask_b32_e32 v0, v0, v5, vcc
	v_sub_u32_e32 v5, v3, v4
	v_cndmask_b32_e32 v3, v3, v5, vcc
	v_add_u32_e32 v5, 1, v0
	v_cmp_ge_u32_e32 vcc, v3, v4
	s_nop 1
	v_cndmask_b32_e32 v0, v0, v5, vcc
	v_mul_lo_u32 v3, v4, v0
	v_add_u32_e32 v3, v3, v4
	v_cmp_ne_u32_e32 vcc, v2, v3
	s_and_saveexec_b64 s[6:7], vcc
	s_xor_b64 s[6:7], exec, s[6:7]
	s_cbranch_execz .LBB0_1825
	s_add_i32 s70, s26, 0x900
	s_lshl_b64 s[8:9], s[70:71], 2
	s_add_u32 s10, s4, s8
	s_addc_u32 s11, s5, s9
	v_mov_b64_e32 v[2:3], s[10:11]
	flat_load_dword v1, v[2:3] sc1
	s_waitcnt vmcnt(0) lgkmcnt(0)
	v_cmp_eq_u32_e32 vcc, v1, v0
	s_and_saveexec_b64 s[8:9], vcc
	s_cbranch_execz .LBB0_1824
	s_mov_b32 s27, 1
	s_mov_b64 s[12:13], 0
	s_branch .LBB0_1816
